# role re-balance after the lockstep change: P2 112 and P3 96 streamer workgroups (four-barrier decode loop)
# speedup vs baseline: 1.0052x; 1.0052x over previous
; __device__ __forceinline__ void sb_decode_stream(Frame& F, unsigned* qctr, int base, int limit) {
;     const float* CK = kin(2); const float* CV = kin(3); const int* PT = (const int*)kin(4);
;     int lane = F.lane; asm volatile("" : "+v"(lane));
;     const int half = lane >> 5, l32 = lane & 31;
;     const float k1 = SB_SCALE * 1.4426950408889634f;
;     const size_t lo = (size_t)half * (NH * HD) + 4 * l32;
;     int it;
;     { const unsigned v = __hip_atomic_fetch_add(qctr, 1u, __ATOMIC_RELAXED, __HIP_MEMORY_SCOPE_AGENT);
;       it = (int)(__builtin_amdgcn_readfirstlane(v) >> 6); if (it >= limit) return; it += base; }
; __global__ void __launch_bounds__(NWAVES * 64, 2) hymba_fwd(Args args) {
;     ...
;         const bool streamer = (F.bid % 3) == 0 && F.bid < 252;
;         if (streamer) sb_decode_stream(F, F.ctl + CW_QUEUE, 0, DEC_Q2);
.LBB0_1119:
	s_cmp_lt_i32 s84, 3
	s_cselect_b64 s[2:3], -1, 0
	s_cmp_gt_i32 s85, 2
	s_cselect_b64 s[4:5], -1, 0
	s_and_b64 s[2:3], s[2:3], s[4:5]
	s_andn2_b64 vcc, exec, s[2:3]
	s_cbranch_vccnz .LBB0_1376
	s_lshr_b32 s2, s96, 3
	s_mov_b32 s3, 0xca5294a5
	s_lshr_b32 s3, s3, s2
	s_and_b32 s3, s3, 1
	s_cmp_eq_u32 s3, 1
	s_cselect_b64 s[42:43], -1, 0
	s_add_u32 s40, s26, 0x1000
	s_addc_u32 s41, s27, 0
	s_add_u32 s38, s26, 0x2ff18000
	s_addc_u32 s39, s27, 0
	s_add_u32 s3, s26, 0x2ff70400
	s_addc_u32 s4, s27, 0
	s_and_b64 vcc, exec, s[42:43]
	s_cbranch_vccz .LBB0_1132
	s_load_dwordx2 s[50:51], s[0:1], 0x10
	s_load_dwordx2 s[52:53], s[0:1], 0x18
	s_load_dwordx2 s[54:55], s[0:1], 0x20
	s_load_dwordx2 s[56:57], s[0:1], 0x60
	s_add_u32 s58, s26, 0x1000
	s_addc_u32 s59, s27, 0
	s_add_u32 s60, s26, 0x2ff18000
	s_addc_u32 s61, s27, 0
	s_add_u32 s62, s26, 0x2ff70400
	s_addc_u32 s63, s27, 0
	s_mov_b32 s76, 0xcccccccc
	s_mov_b32 s77, 0xcccccccc
	s_mov_b32 s78, 0xaaaaaaaa
	s_mov_b32 s79, 0xaaaaaaaa
	v_and_b32_e32 v193, 31, v199
	v_lshrrev_b32_e32 v188, 5, v199
	v_lshlrev_b32_e32 v193, 4, v193
	v_lshl_add_u32 v187, v188, 12, v193
	v_lshlrev_b32_e32 v188, 7, v188
	v_mov_b32_e32 v189, 0
	v_mov_b32_e32 v190, 64
	v_mov_b32_e32 v190, 0x200
	s_mov_b32 s37, 0x251e0
	s_cmp_eq_u32 s94, 0
	s_cbranch_scc0 .Ldqa_pro
	s_mov_b64 exec, 1
	global_atomic_add v191, v189, v190, s[58:59] sc0
	s_mov_b64 exec, -1

; __device__ __forceinline__ void sb_decode_stream(Frame& F, unsigned* qctr, int base, int limit) {
;     const float* CK = kin(2); const float* CV = kin(3); const int* PT = (const int*)kin(4);
;     int lane = F.lane; asm volatile("" : "+v"(lane));
;     const int half = lane >> 5, l32 = lane & 31;
;     const float k1 = SB_SCALE * 1.4426950408889634f;
;     const size_t lo = (size_t)half * (NH * HD) + 4 * l32;
;     int it;
;     { const unsigned v = __hip_atomic_fetch_add(qctr, 1u, __ATOMIC_RELAXED, __HIP_MEMORY_SCOPE_AGENT);
;       it = (int)(__builtin_amdgcn_readfirstlane(v) >> 6); if (it >= limit) return; it += base; }
; __device__ __forceinline__ void p2_mixers(Frame& F, unsigned* qctr) {
;     ...
;     const bool streamer = (F.bid >= NB * NH) && (((F.bid >> 3) - 2) % 5 < 2);
;     if (streamer) sb_decode_stream(F, qctr + 64, DEC_Q2, DEC_ITEMS - DEC_Q2);
.LBB0_1408:
	s_lshr_b32 s2, s96, 3
	s_mov_b32 s3, 0x18c6318c
	s_lshr_b32 s3, s3, s2
	s_and_b32 s3, s3, 1
	s_cmp_eq_u32 s3, 0
	s_cselect_b64 s[6:7], -1, 0
	s_add_u32 s38, s26, 0x1100
	s_addc_u32 s39, s27, 0
	s_add_u32 s3, s26, 0x2ff18000
	s_addc_u32 s4, s27, 0
	s_add_u32 s5, s26, 0x2ff70400
	s_addc_u32 s23, s27, 0
	s_or_b64 s[6:7], s[10:11], s[6:7]
	s_andn2_b64 vcc, exec, s[6:7]
	s_cbranch_vccz .LBB0_1420
	s_load_dwordx2 s[50:51], s[0:1], 0x10
	s_load_dwordx2 s[52:53], s[0:1], 0x18
	s_load_dwordx2 s[54:55], s[0:1], 0x20
	s_load_dwordx2 s[56:57], s[0:1], 0x60
	s_add_u32 s58, s26, 0x1100
	s_addc_u32 s59, s27, 0
	s_add_u32 s60, s26, 0x2ff18000
	s_addc_u32 s61, s27, 0
	s_add_u32 s62, s26, 0x2ff70400
	s_addc_u32 s63, s27, 0
	s_mov_b32 s76, 0xcccccccc
	s_mov_b32 s77, 0xcccccccc
	s_mov_b32 s78, 0xaaaaaaaa
	s_mov_b32 s79, 0xaaaaaaaa
	v_and_b32_e32 v193, 31, v199
	v_lshrrev_b32_e32 v188, 5, v199
	v_lshlrev_b32_e32 v193, 4, v193
	v_lshl_add_u32 v187, v188, 12, v193
	v_lshlrev_b32_e32 v188, 7, v188
	v_mov_b32_e32 v189, 0
	v_mov_b32_e32 v190, 64
	v_mov_b32_e32 v190, 0x200
	s_mov_b32 s37, 0x251e0
	s_cmp_eq_u32 s94, 0
	s_cbranch_scc0 .Ldqc_pro
	s_mov_b64 exec, 1
	global_atomic_add v191, v189, v190, s[58:59] sc0
	s_mov_b64 exec, -1
